# GEMM tile headers zero the accumulators with v_pk_mov_b32 (346 fewer instructions over the six K-loop prologues)
# baseline (speedup 1.0000x reference)
; DI int tid() { int t; asm volatile("v_mov_b32 %0, %1" : "=v"(t) : "v"((int)threadIdx.x)); return t; }
; template <int MB, class Epi>
; DI void gemm_tile(const u16* __restrict__ A, int lda, int row0, int Mrows, const u16* __restrict__ Bt, int ldb, int K, char* smem, Epi& epi, int rot) {
;   char* As = smem;
;   char* Bs = smem + 65536;
;   const unsigned lds_base = (unsigned)(size_t)(lds_char*)smem;
;   const int t = tid(), lane = t & 63, w = __builtin_amdgcn_readfirstlane(t >> 6), wm = w >> 2, wn = w & 3, r = lane & 31, h = lane >> 5;
;   constexpr int NAJ = MB;
;   const int lr = t >> 3;
;   const int lch = (t & 7) ^ ((lr >> 1) & 7);
;   unsigned aoff[NAJ];
; #pragma unroll
;   for (int j = 0; j < NAJ; ++j) {
;     int gr = row0 + lr + 64 * j;
;     gr = gr < 0 ? 0 : (gr > Mrows - 1 ? Mrows - 1 : gr);
;     aoff[j] = (unsigned)gr * (unsigned)lda + lch * 8;
;   }
;   const u16* bp = Bt + (size_t)lr * ldb + lch * 8;
;   f32x16 acc[2][MB];
; #pragma unroll
;   for (int nb = 0; nb < 2; ++nb)
; #pragma unroll
;     for (int mb = 0; mb < MB; ++mb)
; #pragma unroll
;       for (int i = 0; i < 16; ++i) acc[nb][mb][i] = 0.f;
;   const int KT = K >> 6;
;   int kcur = rot % KT;
;     ...
;   GEMM_STAGE(0)
;   asm volatile("s_waitcnt vmcnt(0)" ::: "memory");
;   __syncthreads();
.LBB0_133:
	s_ashr_i32 s0, s13, 3
	s_abs_i32 s3, s0
	s_mul_hi_u32 s9, s3, s19
	s_mul_i32 s10, s9, s12
	s_sub_i32 s3, s3, s10
	s_and_b32 s8, s13, 7
	s_ashr_i32 s2, s13, 31
	s_add_i32 s10, s9, 1
	s_sub_i32 s11, s3, s12
	s_cmp_ge_u32 s3, s12
	s_cselect_b32 s9, s10, s9
	s_cselect_b32 s3, s11, s3
	s_add_i32 s10, s9, 1
	s_cmp_ge_u32 s3, s12
	s_cselect_b32 s3, s10, s9
	s_xor_b32 s3, s3, s2
	s_sub_i32 s3, s3, s2
	s_lshl_b32 s9, s3, 3
	s_or_b32 s8, s9, s8
	s_cmpk_gt_i32 s8, 0x8f
	s_cbranch_scc1 .LBB0_132
	s_mul_i32 s3, s3, s12
	s_sub_i32 s38, s0, s3
	s_lshl_b32 s22, s8, 8
	v_mov_b32 v164, v163
	s_ashr_i32 s39, s38, 31
	v_ashrrev_i32_e32 v2, 3, v164
	v_add_u32_e32 v3, s22, v2
	s_lshl_b64 s[8:9], s[38:39], 19
	v_lshrrev_b32_e32 v0, 4, v164
	v_min_u32_e32 v4, 0x8fff, v3
	s_add_u32 s10, s15, s8
	v_xor_b32_e32 v0, v0, v164
	v_lshlrev_b32_e32 v4, 10, v4
	v_cmp_lt_i32_e32 vcc, -1, v3
	v_min_i32_e32 v6, 0x8fbf, v3
	s_movk_i32 s8, 0xffbf
	v_lshlrev_b32_e32 v0, 3, v0
	v_cndmask_b32_e32 v4, 0, v4, vcc
	v_lshl_add_u32 v6, v6, 10, v202
	v_cmp_lt_i32_e32 vcc, s8, v3
	v_and_b32_e32 v0, 56, v0
	s_movk_i32 s8, 0xff7f
	v_cndmask_b32_e32 v6, 0, v6, vcc
	v_or_b32_e32 v154, v6, v0
	v_min_i32_e32 v6, 0x8f7f, v3
	v_lshl_add_u32 v6, v6, 10, v203
	v_cmp_lt_i32_e32 vcc, s8, v3
	s_movk_i32 s8, 0xff3f
	s_addc_u32 s11, s16, s9
	v_cndmask_b32_e32 v6, 0, v6, vcc
	v_or_b32_e32 v156, v6, v0
	v_min_i32_e32 v6, 0x8f3f, v3
	v_lshl_add_u32 v6, v6, 10, v204
	v_cmp_lt_i32_e32 vcc, s8, v3
	s_lshr_b32 s2, s2, 28
	s_add_i32 s2, s13, s2
	v_cndmask_b32_e32 v3, 0, v6, vcc
	v_or_b32_e32 v6, v3, v0
	v_ashrrev_i32_e32 v3, 31, v2
	v_lshlrev_b64 v[2:3], 11, v[2:3]
	s_and_b32 s2, s2, -16
	v_readfirstlane_b32 s3, v164
	v_lshl_add_u64 v[2:3], s[10:11], 0, v[2:3]
	s_sub_i32 s10, s13, s2
	s_lshl_b32 s26, s10, 6
	s_lshl_b32 s2, s3, 4
	s_bfe_u32 s0, s3, 0x20006
	v_or_b32_e32 v4, v4, v0
	s_ashr_i32 s25, s3, 8
	v_lshlrev_b32_e32 v0, 1, v0
	s_ashr_i32 s27, s26, 31
	s_and_b32 s3, s2, 0xfffffc00
	v_lshl_add_u64 v[158:159], v[2:3], 0, v[0:1]
	s_lshl_b64 s[28:29], s[26:27], 1
	s_add_i32 s11, s3, 0x10000
	v_lshl_add_u64 v[2:3], v[158:159], 0, s[28:29]
	s_add_u32 s28, s84, s28
	s_addc_u32 s29, s85, s29
	v_lshlrev_b32_e32 v0, 1, v4
	v_lshl_add_u64 v[8:9], s[28:29], 0, v[0:1]
	v_mov_b32_e32 v155, v1
	s_mov_b32 m0, s3
	s_nop 0
	global_load_lds_dwordx4 v[8:9], off
	v_lshlrev_b64 v[8:9], 1, v[154:155]
	v_lshl_add_u64 v[10:11], s[28:29], 0, v[8:9]
	v_mov_b32_e32 v157, v1
	s_add_i32 s2, s3, 0x2000
	s_mov_b32 m0, s2
	s_nop 0
	global_load_lds_dwordx4 v[10:11], off
	v_lshlrev_b64 v[10:11], 1, v[156:157]
	v_mov_b32_e32 v7, v1
	v_lshl_add_u64 v[12:13], s[28:29], 0, v[10:11]
	s_add_i32 s2, s3, 0x4000
	s_mov_b32 m0, s2
	s_nop 0
	global_load_lds_dwordx4 v[12:13], off
	v_lshlrev_b64 v[6:7], 1, v[6:7]
	v_lshl_add_u64 v[12:13], s[28:29], 0, v[6:7]
	s_add_i32 s23, s3, 0x6000
	s_mov_b32 m0, s23
	s_nop 0
	global_load_lds_dwordx4 v[12:13], off
	s_mov_b32 m0, s11
	s_nop 0
	global_load_lds_dwordx4 v[2:3], off
	s_add_i32 s2, s3, 0x12000
	v_lshl_add_u64 v[12:13], v[2:3], 0, s[4:5]
	s_mov_b32 m0, s2
	s_nop 0
	global_load_lds_dwordx4 v[12:13], off
	s_add_i32 s2, s3, 0x14000
	v_lshl_add_u64 v[12:13], v[2:3], 0, s[6:7]
	s_mov_b32 m0, s2
	s_nop 0
	global_load_lds_dwordx4 v[12:13], off
	s_add_i32 s2, s3, 0x16000
	v_lshl_add_u64 v[2:3], v[2:3], 0, s[34:35]
	s_mov_b32 m0, s2
	s_nop 0
	global_load_lds_dwordx4 v[2:3], off
	s_lshl_b32 s2, s0, 13
	s_lshl_b32 s8, s25, 14
	s_bitset1_b32 s2, 16
	s_add_i32 s26, s26, 64
	v_lshrrev_b32_e32 v5, 5, v164
	v_and_b32_e32 v165, 31, v164
	v_bfe_u32 v2, v164, 1, 3
	s_cmp_lt_i32 s10, 15
	v_lshlrev_b32_e32 v3, 7, v165
	v_bitop3_b32 v5, v5, v2, 1 bitop3:0x6c
	s_cselect_b32 s26, s26, 0
	v_lshl_or_b32 v5, v5, 4, v3
	s_ashr_i32 s27, s26, 31
	v_bfe_u32 v166, v164, 5, 1
	v_or_b32_e32 v167, s8, v5
	s_lshl_b64 s[26:27], s[26:27], 1
	s_waitcnt vmcnt(0)
	s_barrier
; template <int MB, class Epi>
; DI void gemm_tile(const u16* __restrict__ A, int lda, int row0, int Mrows, const u16* __restrict__ Bt, int ldb, int K, char* smem, Epi& epi, int rot) {
;     ...
;   f32x16 acc[2][MB];
; #pragma unroll
;   for (int nb = 0; nb < 2; ++nb)
; #pragma unroll
;     for (int mb = 0; mb < MB; ++mb)
; #pragma unroll
;       for (int i = 0; i < 16; ++i) acc[nb][mb][i] = 0.f;
;     ...
;   const int sw = (r >> 1) & 7;
;   int foff[4];
; #pragma unroll
;   for (int ks = 0; ks < 4; ++ks) foff[ks] = r * 128 + (((2 * ks + h) ^ sw) << 4);
;   bf8 af[2][MB], bfr[2][2];
;   {
;     const char* as0 = As + wm * (32 * MB) * 128;
;     const char* bs0 = Bs + wn * 64 * 128;
; #pragma unroll
;     for (int mb = 0; mb < MB; ++mb) af[0][mb] = *(const bf8*)(as0 + mb * 32 * 128 + foff[0]);
; #pragma unroll
;     for (int nb = 0; nb < 2; ++nb) bfr[0][nb] = *(const bf8*)(bs0 + nb * 32 * 128 + foff[0]);
;   }
;   const int kbase = rot % KT;
;   if (KT > 1) {
;     const int k1_ = (kbase + 1 >= KT) ? kbase + 1 - KT : kbase + 1;
;     const int ko_ = k1_ * 64;
; #pragma unroll
;     for (int pc = 0; pc < 3; ++pc) GEMM_PIECE(1, pc)
;   }
	v_bitop3_b32 v12, v166, v2, 2 bitop3:0x36
	ds_read_b128 v[146:149], v167
	ds_read_b128 v[142:145], v167 offset:4096
	ds_read_b128 v[134:137], v167 offset:8192
	s_waitcnt vmcnt(0)
	ds_read_b128 v[130:133], v167 offset:12288
	s_add_u32 s26, s84, s26
	v_lshl_or_b32 v171, v12, 4, v3
	v_bitop3_b32 v12, v166, v2, 4 bitop3:0x36
	v_bitop3_b32 v2, v166, v2, 6 bitop3:0x36
	v_or_b32_e32 v168, s2, v5
	s_addc_u32 s27, s85, s27
	v_lshl_or_b32 v170, v12, 4, v3
	v_lshl_or_b32 v169, v2, 4, v3
	ds_read_b128 v[150:153], v168
	ds_read_b128 v[138:141], v168 offset:4096
	s_add_i32 s28, s3, 0x8000
	v_lshl_add_u64 v[2:3], s[26:27], 0, v[0:1]
	s_mov_b32 m0, s28
	s_nop 0
	global_load_lds_dwordx4 v[2:3], off
	v_lshl_add_u64 v[2:3], s[26:27], 0, v[8:9]
	s_add_i32 s28, s3, 0xa000
	s_mov_b32 m0, s28
	s_nop 0
	global_load_lds_dwordx4 v[2:3], off
	v_lshl_add_u64 v[2:3], s[26:27], 0, v[10:11]
	s_add_i32 s26, s3, 0xc000
	s_mov_b32 m0, s26
	s_nop 0
	global_load_lds_dwordx4 v[2:3], off
	v_mov_b32_e32 v2, 0
	s_mov_b32 s9, 0
	v_lshl_add_u64 v[160:161], s[84:85], 0, v[6:7]
	v_lshlrev_b32_e32 v0, 1, v4
	s_mov_b32 s26, s10
	v_mov_b32_e32 v3, v2
	v_pk_mov_b32 v[4:5], v[2:3], v[2:3]
	v_pk_mov_b32 v[6:7], v[2:3], v[2:3]
	v_pk_mov_b32 v[8:9], v[2:3], v[2:3]
	v_pk_mov_b32 v[10:11], v[2:3], v[2:3]
	v_pk_mov_b32 v[12:13], v[2:3], v[2:3]
	v_pk_mov_b32 v[14:15], v[2:3], v[2:3]
	v_pk_mov_b32 v[16:17], v[2:3], v[2:3]
	v_pk_mov_b32 v[18:19], v[2:3], v[2:3]
	v_pk_mov_b32 v[20:21], v[2:3], v[2:3]
	v_pk_mov_b32 v[22:23], v[2:3], v[2:3]
	v_pk_mov_b32 v[24:25], v[2:3], v[2:3]
	v_pk_mov_b32 v[26:27], v[2:3], v[2:3]
	v_pk_mov_b32 v[28:29], v[2:3], v[2:3]
	v_pk_mov_b32 v[30:31], v[2:3], v[2:3]
	v_pk_mov_b32 v[32:33], v[2:3], v[2:3]
	v_pk_mov_b32 v[34:35], v[2:3], v[2:3]
	v_pk_mov_b32 v[36:37], v[2:3], v[2:3]
	v_pk_mov_b32 v[38:39], v[2:3], v[2:3]
	v_pk_mov_b32 v[40:41], v[2:3], v[2:3]
	v_pk_mov_b32 v[42:43], v[2:3], v[2:3]
	v_pk_mov_b32 v[44:45], v[2:3], v[2:3]
	v_pk_mov_b32 v[46:47], v[2:3], v[2:3]
	v_pk_mov_b32 v[48:49], v[2:3], v[2:3]
	v_pk_mov_b32 v[50:51], v[2:3], v[2:3]
	v_pk_mov_b32 v[52:53], v[2:3], v[2:3]
	v_pk_mov_b32 v[54:55], v[2:3], v[2:3]
	v_pk_mov_b32 v[56:57], v[2:3], v[2:3]
	v_pk_mov_b32 v[58:59], v[2:3], v[2:3]
	v_pk_mov_b32 v[60:61], v[2:3], v[2:3]
	v_pk_mov_b32 v[62:63], v[2:3], v[2:3]
	v_pk_mov_b32 v[64:65], v[2:3], v[2:3]
	v_pk_mov_b32 v[66:67], v[2:3], v[2:3]
	v_pk_mov_b32 v[68:69], v[2:3], v[2:3]
	v_pk_mov_b32 v[70:71], v[2:3], v[2:3]
	v_pk_mov_b32 v[72:73], v[2:3], v[2:3]
	v_pk_mov_b32 v[74:75], v[2:3], v[2:3]
	v_pk_mov_b32 v[76:77], v[2:3], v[2:3]
	v_pk_mov_b32 v[78:79], v[2:3], v[2:3]
	v_pk_mov_b32 v[80:81], v[2:3], v[2:3]
	v_pk_mov_b32 v[82:83], v[2:3], v[2:3]
	v_pk_mov_b32 v[84:85], v[2:3], v[2:3]
	v_pk_mov_b32 v[86:87], v[2:3], v[2:3]
	v_pk_mov_b32 v[88:89], v[2:3], v[2:3]
	v_pk_mov_b32 v[90:91], v[2:3], v[2:3]
	v_pk_mov_b32 v[92:93], v[2:3], v[2:3]
	v_pk_mov_b32 v[94:95], v[2:3], v[2:3]
	v_pk_mov_b32 v[96:97], v[2:3], v[2:3]
	v_pk_mov_b32 v[98:99], v[2:3], v[2:3]
	v_pk_mov_b32 v[100:101], v[2:3], v[2:3]
	v_pk_mov_b32 v[102:103], v[2:3], v[2:3]
	v_pk_mov_b32 v[104:105], v[2:3], v[2:3]
	v_pk_mov_b32 v[106:107], v[2:3], v[2:3]
	v_pk_mov_b32 v[108:109], v[2:3], v[2:3]
	v_pk_mov_b32 v[110:111], v[2:3], v[2:3]
	v_pk_mov_b32 v[112:113], v[2:3], v[2:3]
	v_pk_mov_b32 v[114:115], v[2:3], v[2:3]
	v_pk_mov_b32 v[116:117], v[2:3], v[2:3]
	v_pk_mov_b32 v[118:119], v[2:3], v[2:3]
	v_pk_mov_b32 v[120:121], v[2:3], v[2:3]
	v_pk_mov_b32 v[122:123], v[2:3], v[2:3]
	v_pk_mov_b32 v[124:125], v[2:3], v[2:3]
	v_pk_mov_b32 v[126:127], v[2:3], v[2:3]
	v_pk_mov_b32 v[128:129], v[2:3], v[2:3]

; template <int MB, class Epi>
; DI void gemm_tile(const u16* __restrict__ A, int lda, int row0, int Mrows, const u16* __restrict__ Bt, int ldb, int K, char* smem, Epi& epi, int rot) {
;     ...
;   const unsigned lds_base = (unsigned)(size_t)(lds_char*)smem;
;   const int t = tid(), lane = t & 63, w = __builtin_amdgcn_readfirstlane(t >> 6), wm = w >> 2, wn = w & 3, r = lane & 31, h = lane >> 5;
;   constexpr int NAJ = MB;
;   const int lr = t >> 3;
;   const int lch = (t & 7) ^ ((lr >> 1) & 7);
;   unsigned aoff[NAJ];
; #pragma unroll
;   for (int j = 0; j < NAJ; ++j) {
;     int gr = row0 + lr + 64 * j;
;     gr = gr < 0 ? 0 : (gr > Mrows - 1 ? Mrows - 1 : gr);
;     aoff[j] = (unsigned)gr * (unsigned)lda + lch * 8;
;   }
;   const u16* bp = Bt + (size_t)lr * ldb + lch * 8;
;   f32x16 acc[2][MB];
; #pragma unroll
;   for (int nb = 0; nb < 2; ++nb)
; #pragma unroll
;     for (int mb = 0; mb < MB; ++mb)
; #pragma unroll
;       for (int i = 0; i < 16; ++i) acc[nb][mb][i] = 0.f;
;   const int KT = K >> 6;
;   int kcur = rot % KT;
;     ...
;   GEMM_STAGE(0)
;   asm volatile("s_waitcnt vmcnt(0)" ::: "memory");
;   __syncthreads();
;   const int sw = (r >> 1) & 7;
;   int foff[4];
; #pragma unroll
;   for (int ks = 0; ks < 4; ++ks) foff[ks] = r * 128 + (((2 * ks + h) ^ sw) << 4);
;   bf8 af[2][MB], bfr[2][2];
;   {
;     const char* as0 = As + wm * (32 * MB) * 128;
;     const char* bs0 = Bs + wn * 64 * 128;
; #pragma unroll
;     for (int mb = 0; mb < MB; ++mb) af[0][mb] = *(const bf8*)(as0 + mb * 32 * 128 + foff[0]);
; template <int MB>
; DI void phase_res_t(const Params& p, int l, int which, char* smem) {
;     ...
;   const int MT = rows / TR;
;   const u16* A = which ? (const u16*)(p.ws + OFF_ACT) : (const u16*)(p.ws + OFF_QO);
;   const int lda = which ? DFF : 1024, K = which ? DFF : 1024;
;   const u16* W = which ? (const u16*)(p.ws + OFF_WD) + (size_t)l * 1024 * DFF : (const u16*)(p.ws + OFF_WO) + (size_t)l * 1024 * 1024;
;   const float* gate = (const float*)(p.ws + OFF_MODS) + (size_t)l * 17 * 6144 + (which ? 5 : 2) * 1024;
;   for (int tile = bid(); tile < MT * 4; tile += gridDim.x) {
;     int mt, nt;
;     if (!tile_map(tile, 4, MT, mt, nt)) continue;
;     EpiRes<MB> e;
;     e.X = (_Float16*)(p.ws + OFF_X); e.gate = gate; e.row0 = mt * TR; e.n0 = nt * 256; e.ostage = (u16*)smem;
;     gemm_tile<MB>(A, lda, mt * TR, rows, W + (size_t)nt * 256 * K, K, K, smem, e, tile);
.LBB0_647:
	s_ashr_i32 s2, s0, 3
	s_lshr_b32 s3, s2, 30
	s_add_i32 s3, s2, s3
	s_ashr_i32 s3, s3, 2
	s_and_b32 s10, s0, 7
	s_lshl_b32 s11, s3, 3
	s_or_b32 s10, s11, s10
	s_cmpk_gt_i32 s10, 0xbf
	s_cbranch_scc1 .LBB0_646
	s_mulk_i32 s10, 0xc0
	s_waitcnt vmcnt(1)
	v_mov_b32 v124, v163
	s_lshl_b32 s3, s3, 2
	v_ashrrev_i32_e32 v2, 3, v124
	v_lshrrev_b32_e32 v0, 4, v124
	v_xor_b32_e32 v0, v0, v124
	v_add_u32_e32 v3, s10, v2
	s_movk_i32 s11, 0xffc0
	s_sub_i32 s2, s2, s3
	v_lshlrev_b32_e32 v0, 3, v0
	v_med3_i32 v6, v3, s11, v209
	s_movk_i32 s11, 0xff80
	s_ashr_i32 s3, s2, 31
	v_and_b32_e32 v0, 56, v0
	v_med3_i32 v4, v3, 0, v208
	v_med3_i32 v3, v3, s11, v210
	s_lshl_b64 s[12:13], s[2:3], 19
	v_lshl_or_b32 v3, v3, 10, v0
	s_add_u32 s12, s8, s12
	v_add_u32_e32 v122, 0x20000, v3
	v_ashrrev_i32_e32 v3, 31, v2
	s_addc_u32 s13, s9, s13
	v_lshlrev_b64 v[2:3], 11, v[2:3]
	v_lshl_add_u64 v[2:3], s[12:13], 0, v[2:3]
	s_ashr_i32 s12, s0, 31
	s_lshr_b32 s12, s12, 28
	s_add_i32 s12, s0, s12
	s_and_b32 s12, s12, -16
	v_readfirstlane_b32 s14, v124
	s_sub_i32 s16, s0, s12
	s_bfe_u32 s3, s14, 0x20006
	s_ashr_i32 s11, s14, 8
	s_lshl_b32 s12, s16, 6
	s_lshl_b32 s14, s14, 4
	v_lshl_or_b32 v4, v4, 10, v0
	v_lshl_or_b32 v6, v6, 10, v0
	v_lshlrev_b32_e32 v0, 1, v0
	s_ashr_i32 s13, s12, 31
	s_and_b32 s14, s14, 0xfffffc00
	v_lshl_add_u64 v[120:121], v[2:3], 0, v[0:1]
	s_lshl_b64 s[12:13], s[12:13], 1
	s_add_i32 s17, s14, 0x10000
	v_lshl_add_u64 v[2:3], v[120:121], 0, s[12:13]
	s_add_u32 s12, s20, s12
	s_addc_u32 s13, s21, s13
	v_lshlrev_b32_e32 v0, 1, v4
	v_add_u32_e32 v118, 0x10000, v6
	v_lshl_add_u64 v[6:7], s[12:13], 0, v[0:1]
	v_mov_b32_e32 v119, v1
	s_mov_b32 m0, s14
	s_nop 0
	global_load_lds_dwordx4 v[6:7], off
	v_lshlrev_b64 v[6:7], 1, v[118:119]
	v_lshl_add_u64 v[8:9], s[12:13], 0, v[6:7]
	v_mov_b32_e32 v123, v1
	s_add_i32 s18, s14, 0x2000
	s_mov_b32 m0, s18
	s_nop 0
	global_load_lds_dwordx4 v[8:9], off
	v_lshlrev_b64 v[8:9], 1, v[122:123]
	v_lshl_add_u64 v[10:11], s[12:13], 0, v[8:9]
	s_add_i32 s12, s14, 0x4000
	s_mov_b32 m0, s12
	s_nop 0
	global_load_lds_dwordx4 v[10:11], off
	s_mov_b32 m0, s17
	s_nop 0
	global_load_lds_dwordx4 v[2:3], off
	s_add_i32 s12, s14, 0x12000
	v_lshl_add_u64 v[10:11], v[2:3], 0, s[4:5]
	s_mov_b32 m0, s12
	s_nop 0
	global_load_lds_dwordx4 v[10:11], off
	s_add_i32 s12, s14, 0x14000
	v_lshl_add_u64 v[10:11], v[2:3], 0, s[6:7]
	s_mov_b32 m0, s12
	s_nop 0
	global_load_lds_dwordx4 v[10:11], off
	s_add_i32 s12, s14, 0x16000
	v_lshl_add_u64 v[2:3], v[2:3], 0, s[34:35]
	s_mov_b32 m0, s12
	s_nop 0
	global_load_lds_dwordx4 v[2:3], off
	s_lshl_b32 s12, s3, 13
	s_bitset1_b32 s12, 16
	s_cmp_lt_i32 s16, 15
	s_cselect_b32 s18, 0, -16
	s_add_i32 s18, s16, s18
	s_lshl_b32 s18, s18, 6
	v_lshrrev_b32_e32 v5, 5, v124
	v_and_b32_e32 v125, 31, v124
	v_bfe_u32 v2, v124, 1, 3
	s_add_i32 s18, s18, 64
	v_lshlrev_b32_e32 v3, 7, v125
	v_bitop3_b32 v5, v5, v2, 1 bitop3:0x6c
	s_ashr_i32 s19, s18, 31
	s_waitcnt vmcnt(0)
	v_bfe_u32 v126, v124, 5, 1
	v_lshl_or_b32 v5, v5, 4, v3
	s_mul_i32 s13, s11, 0x3000
	s_lshl_b64 s[18:19], s[18:19], 1
	v_bitop3_b32 v10, v126, v2, 2 bitop3:0x36
	v_or_b32_e32 v131, s13, v5
	s_add_u32 s18, s20, s18
	s_waitcnt vmcnt(0)
	s_barrier
	v_lshl_or_b32 v129, v10, 4, v3
	v_bitop3_b32 v10, v126, v2, 4 bitop3:0x36
	v_bitop3_b32 v2, v126, v2, 6 bitop3:0x36
	ds_read_b128 v[110:113], v131
	ds_read_b128 v[106:109], v131 offset:4096
	v_or_b32_e32 v130, s12, v5
	ds_read_b128 v[98:101], v131 offset:8192
	ds_read_b128 v[114:117], v130
	ds_read_b128 v[102:105], v130 offset:4096
	s_addc_u32 s19, s21, s19
	v_lshl_or_b32 v128, v10, 4, v3
	v_lshl_or_b32 v127, v2, 4, v3
	s_add_i32 s22, s14, 0x8000
	v_lshl_add_u64 v[2:3], s[18:19], 0, v[0:1]
	s_mov_b32 m0, s22
	s_nop 0
	global_load_lds_dwordx4 v[2:3], off
	v_lshl_add_u64 v[2:3], s[18:19], 0, v[6:7]
	s_add_i32 s22, s14, 0xa000
	s_mov_b32 m0, s22
	s_nop 0
	global_load_lds_dwordx4 v[2:3], off
	v_lshl_add_u64 v[2:3], s[18:19], 0, v[8:9]
	s_add_i32 s18, s14, 0xc000
	s_mov_b32 m0, s18
	s_nop 0
	global_load_lds_dwordx4 v[2:3], off
	v_mov_b32_e32 v34, 0
	s_mov_b32 s15, 0
	v_lshlrev_b32_e32 v0, 1, v4
	s_mov_b32 s22, 0
	v_mov_b32_e32 v35, v34
	v_pk_mov_b32 v[2:3], v[34:35], v[34:35]
	v_pk_mov_b32 v[4:5], v[34:35], v[34:35]
	v_pk_mov_b32 v[6:7], v[34:35], v[34:35]
	v_pk_mov_b32 v[8:9], v[34:35], v[34:35]
	v_pk_mov_b32 v[10:11], v[34:35], v[34:35]
	v_pk_mov_b32 v[12:13], v[34:35], v[34:35]
	v_pk_mov_b32 v[14:15], v[34:35], v[34:35]
	v_pk_mov_b32 v[16:17], v[34:35], v[34:35]
	v_pk_mov_b32 v[18:19], v[34:35], v[34:35]
	v_pk_mov_b32 v[20:21], v[34:35], v[34:35]
	v_pk_mov_b32 v[22:23], v[34:35], v[34:35]
	v_pk_mov_b32 v[24:25], v[34:35], v[34:35]
	v_pk_mov_b32 v[26:27], v[34:35], v[34:35]
	v_pk_mov_b32 v[28:29], v[34:35], v[34:35]
	v_pk_mov_b32 v[30:31], v[34:35], v[34:35]
	v_pk_mov_b32 v[32:33], v[34:35], v[34:35]
	v_pk_mov_b32 v[36:37], v[34:35], v[34:35]
	v_pk_mov_b32 v[38:39], v[34:35], v[34:35]
	v_pk_mov_b32 v[40:41], v[34:35], v[34:35]
	v_pk_mov_b32 v[42:43], v[34:35], v[34:35]
	v_pk_mov_b32 v[44:45], v[34:35], v[34:35]
	v_pk_mov_b32 v[46:47], v[34:35], v[34:35]
	v_pk_mov_b32 v[48:49], v[34:35], v[34:35]
	v_pk_mov_b32 v[50:51], v[34:35], v[34:35]
	v_pk_mov_b32 v[52:53], v[34:35], v[34:35]
	v_pk_mov_b32 v[54:55], v[34:35], v[34:35]
	v_pk_mov_b32 v[56:57], v[34:35], v[34:35]
	v_pk_mov_b32 v[58:59], v[34:35], v[34:35]
	v_pk_mov_b32 v[60:61], v[34:35], v[34:35]
	v_pk_mov_b32 v[62:63], v[34:35], v[34:35]
	v_pk_mov_b32 v[64:65], v[34:35], v[34:35]
	v_pk_mov_b32 v[66:67], v[34:35], v[34:35]
	v_pk_mov_b32 v[68:69], v[34:35], v[34:35]
	v_pk_mov_b32 v[70:71], v[34:35], v[34:35]
	v_pk_mov_b32 v[72:73], v[34:35], v[34:35]
	v_pk_mov_b32 v[74:75], v[34:35], v[34:35]
	v_pk_mov_b32 v[76:77], v[34:35], v[34:35]
	v_pk_mov_b32 v[78:79], v[34:35], v[34:35]
	v_pk_mov_b32 v[80:81], v[34:35], v[34:35]
	v_pk_mov_b32 v[82:83], v[34:35], v[34:35]
	v_pk_mov_b32 v[84:85], v[34:35], v[34:35]
	v_pk_mov_b32 v[86:87], v[34:35], v[34:35]
	v_pk_mov_b32 v[88:89], v[34:35], v[34:35]
	v_pk_mov_b32 v[90:91], v[34:35], v[34:35]
	v_pk_mov_b32 v[92:93], v[34:35], v[34:35]
	v_pk_mov_b32 v[94:95], v[34:35], v[34:35]
	v_pk_mov_b32 v[96:97], v[34:35], v[34:35]

; DI int tid() { int t; asm volatile("v_mov_b32 %0, %1" : "=v"(t) : "v"((int)threadIdx.x)); return t; }
; DI int bid() { int b; asm volatile("s_mov_b32 %0, %1" : "=s"(b) : "s"((int)blockIdx.x)); return b; }
; template <int MB, class Epi>
; DI void gemm_tile(const u16* __restrict__ A, int lda, int row0, int Mrows, const u16* __restrict__ Bt, int ldb, int K, char* smem, Epi& epi, int rot) {
;     ...
;   const unsigned lds_base = (unsigned)(size_t)(lds_char*)smem;
;   const int t = tid(), lane = t & 63, w = __builtin_amdgcn_readfirstlane(t >> 6), wm = w >> 2, wn = w & 3, r = lane & 31, h = lane >> 5;
;   constexpr int NAJ = MB;
;   const int lr = t >> 3;
;   const int lch = (t & 7) ^ ((lr >> 1) & 7);
;   unsigned aoff[NAJ];
; #pragma unroll
;   for (int j = 0; j < NAJ; ++j) {
;     int gr = row0 + lr + 64 * j;
;     gr = gr < 0 ? 0 : (gr > Mrows - 1 ? Mrows - 1 : gr);
;     aoff[j] = (unsigned)gr * (unsigned)lda + lch * 8;
;   }
;   const u16* bp = Bt + (size_t)lr * ldb + lch * 8;
;   f32x16 acc[2][MB];
; #pragma unroll
;   for (int nb = 0; nb < 2; ++nb)
; #pragma unroll
;     for (int mb = 0; mb < MB; ++mb)
; #pragma unroll
;       for (int i = 0; i < 16; ++i) acc[nb][mb][i] = 0.f;
;   const int KT = K >> 6;
;   int kcur = rot % KT;
;     ...
;   GEMM_STAGE(0)
;   asm volatile("s_waitcnt vmcnt(0)" ::: "memory");
;   __syncthreads();
; template <int MB>
; DI void phase_res_t(const Params& p, int l, int which, char* smem) {
;     ...
;   for (int tile = bid(); tile < MT * 4; tile += gridDim.x) {
;     int mt, nt;
;     if (!tile_map(tile, 4, MT, mt, nt)) continue;
;     EpiRes<MB> e;
;     e.X = (_Float16*)(p.ws + OFF_X); e.gate = gate; e.row0 = mt * TR; e.n0 = nt * 256; e.ostage = (u16*)smem;
;     gemm_tile<MB>(A, lda, mt * TR, rows, W + (size_t)nt * 256 * K, K, K, smem, e, tile);
.LBB0_655:
	s_cmpk_gt_i32 s0, 0x1ff
	s_cbranch_scc1 .LBB0_660
	s_ashr_i32 s2, s0, 3
	s_lshr_b32 s3, s2, 30
	s_add_i32 s3, s2, s3
	s_ashr_i32 s3, s3, 2
	s_and_b32 s8, s0, 7
	s_lshl_b32 s9, s3, 3
	s_or_b32 s8, s9, s8
	s_cmpk_gt_i32 s8, 0x7f
	s_cbranch_scc1 .LBB0_654
	s_lshl_b32 s3, s3, 2
	s_sub_i32 s36, s2, s3
	s_ashr_i32 s37, s36, 31
	v_mov_b32 v164, v163
	s_lshl_b32 s2, s8, 8
	v_lshrrev_b32_e32 v0, 4, v164
	s_lshl_b64 s[8:9], s[36:37], 19
	v_readlane_b32 s3, v234, 2
	v_ashrrev_i32_e32 v2, 3, v164
	v_xor_b32_e32 v0, v0, v164
	s_add_u32 s12, s3, s8
	v_add_u32_e32 v3, s2, v2
	v_lshlrev_b32_e32 v0, 3, v0
	s_movk_i32 s8, 0xffc0
	v_and_b32_e32 v0, 56, v0
	v_med3_i32 v6, v3, s8, v212
	v_lshl_or_b32 v6, v6, 10, v0
	s_movk_i32 s8, 0xff80
	v_readlane_b32 s3, v234, 3
	v_add_u32_e32 v154, 0x10000, v6
	v_med3_i32 v6, v3, s8, v213
	s_movk_i32 s8, 0xff40
	s_addc_u32 s13, s3, s9
	v_med3_i32 v4, v3, 0, v211
	v_med3_i32 v3, v3, s8, v214
	s_ashr_i32 s10, s0, 31
	v_lshl_or_b32 v6, v6, 10, v0
	v_lshl_or_b32 v3, v3, 10, v0
	s_lshr_b32 s10, s10, 28
	v_add_u32_e32 v156, 0x20000, v6
	v_add_u32_e32 v6, 0x30000, v3
	v_ashrrev_i32_e32 v3, 31, v2
	s_add_i32 s10, s0, s10
	v_lshlrev_b64 v[2:3], 11, v[2:3]
	s_and_b32 s10, s10, -16
	v_lshl_add_u64 v[2:3], s[12:13], 0, v[2:3]
	s_sub_i32 s13, s0, s10
	v_readfirstlane_b32 s9, v164
	s_lshl_b32 s14, s13, 6
	s_bfe_u32 s3, s9, 0x20006
	s_ashr_i32 s8, s9, 8
	s_ashr_i32 s15, s14, 31
	s_lshl_b32 s9, s9, 4
	v_lshl_or_b32 v4, v4, 10, v0
	v_lshlrev_b32_e32 v0, 1, v0
	s_lshl_b64 s[16:17], s[14:15], 1
	s_and_b32 s14, s9, 0xfffffc00
	v_lshl_add_u64 v[158:159], v[2:3], 0, v[0:1]
	s_add_i32 s12, s14, 0x10000
	v_lshl_add_u64 v[2:3], v[158:159], 0, s[16:17]
	s_add_u32 s16, s20, s16
	s_addc_u32 s17, s21, s17
	v_lshlrev_b32_e32 v0, 1, v4
	v_lshl_add_u64 v[8:9], s[16:17], 0, v[0:1]
	v_mov_b32_e32 v155, v1
	s_mov_b32 m0, s14
	s_nop 0
	global_load_lds_dwordx4 v[8:9], off
	v_lshlrev_b64 v[8:9], 1, v[154:155]
	v_lshl_add_u64 v[10:11], s[16:17], 0, v[8:9]
	v_mov_b32_e32 v157, v1
	s_add_i32 s9, s14, 0x2000
	s_mov_b32 m0, s9
	s_nop 0
	global_load_lds_dwordx4 v[10:11], off
	v_lshlrev_b64 v[10:11], 1, v[156:157]
	v_mov_b32_e32 v7, v1
	v_lshl_add_u64 v[12:13], s[16:17], 0, v[10:11]
	s_add_i32 s9, s14, 0x4000
	s_mov_b32 m0, s9
	s_nop 0
	global_load_lds_dwordx4 v[12:13], off
	v_lshlrev_b64 v[6:7], 1, v[6:7]
	v_lshl_add_u64 v[12:13], s[16:17], 0, v[6:7]
	s_add_i32 s15, s14, 0x6000
	s_mov_b32 m0, s15
	s_nop 0
	global_load_lds_dwordx4 v[12:13], off
	s_mov_b32 m0, s12
	s_nop 0
	global_load_lds_dwordx4 v[2:3], off
	s_add_i32 s9, s14, 0x12000
	v_lshl_add_u64 v[12:13], v[2:3], 0, s[4:5]
	s_mov_b32 m0, s9
	s_nop 0
	global_load_lds_dwordx4 v[12:13], off
	s_add_i32 s9, s14, 0x14000
	v_lshl_add_u64 v[12:13], v[2:3], 0, s[6:7]
	s_mov_b32 m0, s9
	s_nop 0
	global_load_lds_dwordx4 v[12:13], off
	s_add_i32 s9, s14, 0x16000
	v_lshl_add_u64 v[2:3], v[2:3], 0, s[34:35]
	s_mov_b32 m0, s9
	s_nop 0
	global_load_lds_dwordx4 v[2:3], off
	s_lshl_b32 s9, s3, 13
	s_lshl_b32 s10, s8, 14
	s_bitset1_b32 s9, 16
	s_cmp_lt_i32 s13, 15
	s_cselect_b32 s16, 0, -16
	s_add_i32 s16, s13, s16
	v_lshrrev_b32_e32 v5, 5, v164
	v_and_b32_e32 v165, 31, v164
	v_bfe_u32 v2, v164, 1, 3
	s_lshl_b32 s16, s16, 6
	v_lshlrev_b32_e32 v3, 7, v165
	v_bitop3_b32 v5, v5, v2, 1 bitop3:0x6c
	s_add_i32 s16, s16, 64
	v_lshl_or_b32 v5, v5, 4, v3
	s_ashr_i32 s17, s16, 31
	v_bfe_u32 v166, v164, 5, 1
	v_or_b32_e32 v168, s10, v5
	s_lshl_b64 s[16:17], s[16:17], 1
	s_waitcnt vmcnt(0)
	s_barrier
; template <int MB, class Epi>
; DI void gemm_tile(const u16* __restrict__ A, int lda, int row0, int Mrows, const u16* __restrict__ Bt, int ldb, int K, char* smem, Epi& epi, int rot) {
;     ...
;   f32x16 acc[2][MB];
; #pragma unroll
;   for (int nb = 0; nb < 2; ++nb)
; #pragma unroll
;     for (int mb = 0; mb < MB; ++mb)
; #pragma unroll
;       for (int i = 0; i < 16; ++i) acc[nb][mb][i] = 0.f;
;     ...
;   const int sw = (r >> 1) & 7;
;   int foff[4];
; #pragma unroll
;   for (int ks = 0; ks < 4; ++ks) foff[ks] = r * 128 + (((2 * ks + h) ^ sw) << 4);
;   bf8 af[2][MB], bfr[2][2];
;   {
;     const char* as0 = As + wm * (32 * MB) * 128;
;     const char* bs0 = Bs + wn * 64 * 128;
; #pragma unroll
;     for (int mb = 0; mb < MB; ++mb) af[0][mb] = *(const bf8*)(as0 + mb * 32 * 128 + foff[0]);
; #pragma unroll
;     for (int nb = 0; nb < 2; ++nb) bfr[0][nb] = *(const bf8*)(bs0 + nb * 32 * 128 + foff[0]);
;   }
;   const int kbase = rot % KT;
;   if (KT > 1) {
;     const int k1_ = (kbase + 1 >= KT) ? kbase + 1 - KT : kbase + 1;
;     const int ko_ = k1_ * 64;
; #pragma unroll
;     for (int pc = 0; pc < 3; ++pc) GEMM_PIECE(1, pc)
;   }
	v_bitop3_b32 v12, v166, v2, 2 bitop3:0x36
	ds_read_b128 v[146:149], v168
	ds_read_b128 v[142:145], v168 offset:4096
	ds_read_b128 v[134:137], v168 offset:8192
	s_waitcnt vmcnt(0)
	ds_read_b128 v[130:133], v168 offset:12288
	s_add_u32 s16, s20, s16
	v_lshl_or_b32 v171, v12, 4, v3
	v_bitop3_b32 v12, v166, v2, 4 bitop3:0x36
	v_bitop3_b32 v2, v166, v2, 6 bitop3:0x36
	v_or_b32_e32 v167, s9, v5
	s_addc_u32 s17, s21, s17
	v_lshl_or_b32 v170, v12, 4, v3
	v_lshl_or_b32 v169, v2, 4, v3
	ds_read_b128 v[150:153], v167
	ds_read_b128 v[138:141], v167 offset:4096
	s_add_i32 s18, s14, 0x8000
	v_lshl_add_u64 v[2:3], s[16:17], 0, v[0:1]
	s_mov_b32 m0, s18
	s_nop 0
	global_load_lds_dwordx4 v[2:3], off
	v_lshl_add_u64 v[2:3], s[16:17], 0, v[8:9]
	s_add_i32 s18, s14, 0xa000
	s_mov_b32 m0, s18
	s_nop 0
	global_load_lds_dwordx4 v[2:3], off
	v_lshl_add_u64 v[2:3], s[16:17], 0, v[10:11]
	s_add_i32 s16, s14, 0xc000
	s_mov_b32 m0, s16
	s_nop 0
	global_load_lds_dwordx4 v[2:3], off
	v_mov_b32_e32 v2, 0
	s_mov_b32 s11, 0
	v_lshl_add_u64 v[160:161], s[20:21], 0, v[6:7]
	v_lshlrev_b32_e32 v0, 1, v4
	s_mov_b32 s17, 0
	v_mov_b32_e32 v3, v2
	v_pk_mov_b32 v[4:5], v[2:3], v[2:3]
	v_pk_mov_b32 v[6:7], v[2:3], v[2:3]
	v_pk_mov_b32 v[8:9], v[2:3], v[2:3]
	v_pk_mov_b32 v[10:11], v[2:3], v[2:3]
	v_pk_mov_b32 v[12:13], v[2:3], v[2:3]
	v_pk_mov_b32 v[14:15], v[2:3], v[2:3]
	v_pk_mov_b32 v[16:17], v[2:3], v[2:3]
	v_pk_mov_b32 v[18:19], v[2:3], v[2:3]
	v_pk_mov_b32 v[20:21], v[2:3], v[2:3]
	v_pk_mov_b32 v[22:23], v[2:3], v[2:3]
	v_pk_mov_b32 v[24:25], v[2:3], v[2:3]
	v_pk_mov_b32 v[26:27], v[2:3], v[2:3]
	v_pk_mov_b32 v[28:29], v[2:3], v[2:3]
	v_pk_mov_b32 v[30:31], v[2:3], v[2:3]
	v_pk_mov_b32 v[32:33], v[2:3], v[2:3]
	v_pk_mov_b32 v[34:35], v[2:3], v[2:3]
	v_pk_mov_b32 v[36:37], v[2:3], v[2:3]
	v_pk_mov_b32 v[38:39], v[2:3], v[2:3]
	v_pk_mov_b32 v[40:41], v[2:3], v[2:3]
	v_pk_mov_b32 v[42:43], v[2:3], v[2:3]
	v_pk_mov_b32 v[44:45], v[2:3], v[2:3]
	v_pk_mov_b32 v[46:47], v[2:3], v[2:3]
	v_pk_mov_b32 v[48:49], v[2:3], v[2:3]
	v_pk_mov_b32 v[50:51], v[2:3], v[2:3]
	v_pk_mov_b32 v[52:53], v[2:3], v[2:3]
	v_pk_mov_b32 v[54:55], v[2:3], v[2:3]
	v_pk_mov_b32 v[56:57], v[2:3], v[2:3]
	v_pk_mov_b32 v[58:59], v[2:3], v[2:3]
	v_pk_mov_b32 v[60:61], v[2:3], v[2:3]
	v_pk_mov_b32 v[62:63], v[2:3], v[2:3]
	v_pk_mov_b32 v[64:65], v[2:3], v[2:3]
	v_pk_mov_b32 v[66:67], v[2:3], v[2:3]
	v_pk_mov_b32 v[68:69], v[2:3], v[2:3]
	v_pk_mov_b32 v[70:71], v[2:3], v[2:3]
	v_pk_mov_b32 v[72:73], v[2:3], v[2:3]
	v_pk_mov_b32 v[74:75], v[2:3], v[2:3]
	v_pk_mov_b32 v[76:77], v[2:3], v[2:3]
	v_pk_mov_b32 v[78:79], v[2:3], v[2:3]
	v_pk_mov_b32 v[80:81], v[2:3], v[2:3]
	v_pk_mov_b32 v[82:83], v[2:3], v[2:3]
	v_pk_mov_b32 v[84:85], v[2:3], v[2:3]
	v_pk_mov_b32 v[86:87], v[2:3], v[2:3]
	v_pk_mov_b32 v[88:89], v[2:3], v[2:3]
	v_pk_mov_b32 v[90:91], v[2:3], v[2:3]
	v_pk_mov_b32 v[92:93], v[2:3], v[2:3]
	v_pk_mov_b32 v[94:95], v[2:3], v[2:3]
	v_pk_mov_b32 v[96:97], v[2:3], v[2:3]
	v_pk_mov_b32 v[98:99], v[2:3], v[2:3]
	v_pk_mov_b32 v[100:101], v[2:3], v[2:3]
	v_pk_mov_b32 v[102:103], v[2:3], v[2:3]
	v_pk_mov_b32 v[104:105], v[2:3], v[2:3]
	v_pk_mov_b32 v[106:107], v[2:3], v[2:3]
	v_pk_mov_b32 v[108:109], v[2:3], v[2:3]
	v_pk_mov_b32 v[110:111], v[2:3], v[2:3]
	v_pk_mov_b32 v[112:113], v[2:3], v[2:3]
	v_pk_mov_b32 v[114:115], v[2:3], v[2:3]
	v_pk_mov_b32 v[116:117], v[2:3], v[2:3]
	v_pk_mov_b32 v[118:119], v[2:3], v[2:3]
	v_pk_mov_b32 v[120:121], v[2:3], v[2:3]
	v_pk_mov_b32 v[122:123], v[2:3], v[2:3]
	v_pk_mov_b32 v[124:125], v[2:3], v[2:3]
	v_pk_mov_b32 v[126:127], v[2:3], v[2:3]
	v_pk_mov_b32 v[128:129], v[2:3], v[2:3]

; DI int crow(int i, int h) { return (i & 3) + 8 * (i >> 2) + 4 * h; }
; template <int MB, class Epi>
; DI void gemm_tile(const u16* __restrict__ A, int lda, int row0, int Mrows, const u16* __restrict__ Bt, int ldb, int K, char* smem, Epi& epi, int rot) {
;     ...
;   const int sw = (r >> 1) & 7;
;   int foff[4];
; #pragma unroll
;   for (int ks = 0; ks < 4; ++ks) foff[ks] = r * 128 + (((2 * ks + h) ^ sw) << 4);
;   bf8 af[2][MB], bfr[2][2];
;   {
;     const char* as0 = As + wm * (32 * MB) * 128;
;     const char* bs0 = Bs + wn * 64 * 128;
; #pragma unroll
;     for (int mb = 0; mb < MB; ++mb) af[0][mb] = *(const bf8*)(as0 + mb * 32 * 128 + foff[0]);
; #pragma unroll
;     for (int nb = 0; nb < 2; ++nb) bfr[0][nb] = *(const bf8*)(bs0 + nb * 32 * 128 + foff[0]);
;   }
;   const int kbase = rot % KT;
;   if (KT > 1) {
;     const int k1_ = (kbase + 1 >= KT) ? kbase + 1 - KT : kbase + 1;
;     const int ko_ = k1_ * 64;
; #pragma unroll
;     for (int pc = 0; pc < 3; ++pc) GEMM_PIECE(1, pc)
;   }
;   DI void operator()(f32x16 (&acc)[2][4], int wm, int wn, int r, int h) {
;     ...
;             const int ff = nt * 128 + wn * 32 + crow(i0, h) + nb * DFF;
;             const f32x2n a0 = *(const f32x2n*)(cw + ff), a1 = *(const f32x2n*)(cw + 2 * DFF + ff), a2 = *(const f32x2n*)(cw + 4 * DFF + ff),
;                          a3 = *(const f32x2n*)(cb + ff);
;             w0[0] = a0.x; w0[1] = a0.y; w1[0] = a1.x; w1[1] = a1.y; w2[0] = a2.x; w2[1] = a2.y; bz[0] = a3.x; bz[1] = a3.y;
.Lupd_w0:
	s_barrier
	v_bitop3_b32 v7, v169, v2, 2 bitop3:0x36
	ds_read_b128 v[146:149], v164
	ds_read_b128 v[142:145], v164 offset:4096
	ds_read_b128 v[134:137], v164 offset:8192
	ds_read_b128 v[130:133], v164 offset:12288
	s_add_u32 s28, s84, s28
	v_lshl_or_b32 v171, v7, 4, v3
	v_bitop3_b32 v7, v169, v2, 4 bitop3:0x36
	v_bitop3_b32 v2, v169, v2, 6 bitop3:0x36
	v_or_b32_e32 v166, s2, v5
	s_addc_u32 s29, s85, s29
	v_lshl_or_b32 v170, v7, 4, v3
	v_lshl_or_b32 v168, v2, 4, v3
	ds_read_b128 v[150:153], v166
	ds_read_b128 v[138:141], v166 offset:4096
	s_lshl_b32 s100, s48, 9
	s_lshl_b32 s101, s16, 7
	s_add_i32 s100, s100, s101
	v_lshlrev_b32_e32 v248, 2, v167
	v_add_u32_e32 v248, s100, v248
	v_add_u32_e32 v249, 0x2c00, v248
	global_load_dword v241, v248, s[40:41]
	global_load_dword v242, v248, s[44:45]
	global_load_dword v240, v248, s[46:47]
	global_load_dword v244, v248, s[42:43]
	global_load_dword v247, v249, s[40:41]
	global_load_dword v250, v249, s[44:45]
	global_load_dword v246, v249, s[46:47]
	global_load_dword v252, v249, s[42:43]
	s_add_i32 s25, s3, 0x8000
	v_lshl_add_u64 v[2:3], s[28:29], 0, v[0:1]
	s_mov_b32 m0, s25
	s_nop 0
	global_load_lds_dwordx4 v[2:3], off
	v_lshl_add_u64 v[2:3], s[28:29], 0, v[10:11]
	s_add_i32 s25, s3, 0xa000
	s_mov_b32 m0, s25
	s_nop 0
	global_load_lds_dwordx4 v[2:3], off
	v_lshl_add_u64 v[2:3], s[28:29], 0, v[12:13]
	s_add_i32 s25, s3, 0xc000
	s_mov_b32 m0, s25
	s_nop 0
	global_load_lds_dwordx4 v[2:3], off
	v_mov_b32_e32 v2, 0
	s_mov_b32 s18, 0
	v_lshl_add_u64 v[156:157], s[84:85], 0, v[14:15]
	v_lshlrev_b32_e32 v0, 1, v4
	v_lshlrev_b32_e32 v158, 1, v6
	v_lshlrev_b32_e32 v160, 1, v8
	s_mov_b32 s25, s19
	v_mov_b32_e32 v3, v2
	v_pk_mov_b32 v[4:5], v[2:3], v[2:3]
	v_pk_mov_b32 v[6:7], v[2:3], v[2:3]
	v_pk_mov_b32 v[8:9], v[2:3], v[2:3]
	v_pk_mov_b32 v[10:11], v[2:3], v[2:3]
	v_pk_mov_b32 v[12:13], v[2:3], v[2:3]
	v_pk_mov_b32 v[14:15], v[2:3], v[2:3]
	v_pk_mov_b32 v[16:17], v[2:3], v[2:3]
	v_pk_mov_b32 v[18:19], v[2:3], v[2:3]
	v_pk_mov_b32 v[20:21], v[2:3], v[2:3]
	v_pk_mov_b32 v[22:23], v[2:3], v[2:3]
	v_pk_mov_b32 v[24:25], v[2:3], v[2:3]
	v_pk_mov_b32 v[26:27], v[2:3], v[2:3]
	v_pk_mov_b32 v[28:29], v[2:3], v[2:3]
	v_pk_mov_b32 v[30:31], v[2:3], v[2:3]
	v_pk_mov_b32 v[32:33], v[2:3], v[2:3]
	v_pk_mov_b32 v[34:35], v[2:3], v[2:3]
	v_pk_mov_b32 v[36:37], v[2:3], v[2:3]
	v_pk_mov_b32 v[38:39], v[2:3], v[2:3]
	v_pk_mov_b32 v[40:41], v[2:3], v[2:3]
	v_pk_mov_b32 v[42:43], v[2:3], v[2:3]
	v_pk_mov_b32 v[44:45], v[2:3], v[2:3]
	v_pk_mov_b32 v[46:47], v[2:3], v[2:3]
	v_pk_mov_b32 v[48:49], v[2:3], v[2:3]
	v_pk_mov_b32 v[50:51], v[2:3], v[2:3]
	v_pk_mov_b32 v[52:53], v[2:3], v[2:3]
	v_pk_mov_b32 v[54:55], v[2:3], v[2:3]
	v_pk_mov_b32 v[56:57], v[2:3], v[2:3]
	v_pk_mov_b32 v[58:59], v[2:3], v[2:3]
	v_pk_mov_b32 v[60:61], v[2:3], v[2:3]
	v_pk_mov_b32 v[62:63], v[2:3], v[2:3]
	v_pk_mov_b32 v[64:65], v[2:3], v[2:3]
	v_pk_mov_b32 v[66:67], v[2:3], v[2:3]
	v_pk_mov_b32 v[68:69], v[2:3], v[2:3]
	v_pk_mov_b32 v[70:71], v[2:3], v[2:3]
	v_pk_mov_b32 v[72:73], v[2:3], v[2:3]
	v_pk_mov_b32 v[74:75], v[2:3], v[2:3]
	v_pk_mov_b32 v[76:77], v[2:3], v[2:3]
	v_pk_mov_b32 v[78:79], v[2:3], v[2:3]
	v_pk_mov_b32 v[80:81], v[2:3], v[2:3]
	v_pk_mov_b32 v[82:83], v[2:3], v[2:3]
	v_pk_mov_b32 v[84:85], v[2:3], v[2:3]
	v_pk_mov_b32 v[86:87], v[2:3], v[2:3]
	v_pk_mov_b32 v[88:89], v[2:3], v[2:3]
	v_pk_mov_b32 v[90:91], v[2:3], v[2:3]
	v_pk_mov_b32 v[92:93], v[2:3], v[2:3]
	v_pk_mov_b32 v[94:95], v[2:3], v[2:3]
	v_pk_mov_b32 v[96:97], v[2:3], v[2:3]
	v_pk_mov_b32 v[98:99], v[2:3], v[2:3]
	v_pk_mov_b32 v[100:101], v[2:3], v[2:3]
	v_pk_mov_b32 v[102:103], v[2:3], v[2:3]
	v_pk_mov_b32 v[104:105], v[2:3], v[2:3]
	v_pk_mov_b32 v[106:107], v[2:3], v[2:3]
	v_pk_mov_b32 v[108:109], v[2:3], v[2:3]
	v_pk_mov_b32 v[110:111], v[2:3], v[2:3]
	v_pk_mov_b32 v[112:113], v[2:3], v[2:3]
	v_pk_mov_b32 v[114:115], v[2:3], v[2:3]
	v_pk_mov_b32 v[116:117], v[2:3], v[2:3]
	v_pk_mov_b32 v[118:119], v[2:3], v[2:3]
	v_pk_mov_b32 v[120:121], v[2:3], v[2:3]
	v_pk_mov_b32 v[122:123], v[2:3], v[2:3]
	v_pk_mov_b32 v[124:125], v[2:3], v[2:3]
	v_pk_mov_b32 v[126:127], v[2:3], v[2:3]
	v_pk_mov_b32 v[128:129], v[2:3], v[2:3]

; template <int MB, class Epi>
; DI void gemm_tile(const u16* __restrict__ A, int lda, int row0, int Mrows, const u16* __restrict__ Bt, int ldb, int K, char* smem, Epi& epi, int rot) {
;     ...
;   const unsigned lds_base = (unsigned)(size_t)(lds_char*)smem;
;   const int t = tid(), lane = t & 63, w = __builtin_amdgcn_readfirstlane(t >> 6), wm = w >> 2, wn = w & 3, r = lane & 31, h = lane >> 5;
;   constexpr int NAJ = MB;
;   const int lr = t >> 3;
;   const int lch = (t & 7) ^ ((lr >> 1) & 7);
;   unsigned aoff[NAJ];
; #pragma unroll
;   for (int j = 0; j < NAJ; ++j) {
;     int gr = row0 + lr + 64 * j;
;     gr = gr < 0 ? 0 : (gr > Mrows - 1 ? Mrows - 1 : gr);
;     aoff[j] = (unsigned)gr * (unsigned)lda + lch * 8;
;   }
;   const u16* bp = Bt + (size_t)lr * ldb + lch * 8;
;   f32x16 acc[2][MB];
; #pragma unroll
;   for (int nb = 0; nb < 2; ++nb)
; #pragma unroll
;     for (int mb = 0; mb < MB; ++mb)
; #pragma unroll
;       for (int i = 0; i < 16; ++i) acc[nb][mb][i] = 0.f;
;   const int KT = K >> 6;
;   int kcur = rot % KT;
;     ...
;   GEMM_STAGE(0)
;   asm volatile("s_waitcnt vmcnt(0)" ::: "memory");
;   __syncthreads();
;   const int sw = (r >> 1) & 7;
;   int foff[4];
; #pragma unroll
;   for (int ks = 0; ks < 4; ++ks) foff[ks] = r * 128 + (((2 * ks + h) ^ sw) << 4);
;   bf8 af[2][MB], bfr[2][2];
;   {
;     const char* as0 = As + wm * (32 * MB) * 128;
;     const char* bs0 = Bs + wn * 64 * 128;
; #pragma unroll
;     for (int mb = 0; mb < MB; ++mb) af[0][mb] = *(const bf8*)(as0 + mb * 32 * 128 + foff[0]);
; template <int MB>
; DI void phase_res_t(const Params& p, int l, int which, char* smem) {
;     ...
;   const int MT = rows / TR;
;   const u16* A = which ? (const u16*)(p.ws + OFF_ACT) : (const u16*)(p.ws + OFF_QO);
;   const int lda = which ? DFF : 1024, K = which ? DFF : 1024;
;   const u16* W = which ? (const u16*)(p.ws + OFF_WD) + (size_t)l * 1024 * DFF : (const u16*)(p.ws + OFF_WO) + (size_t)l * 1024 * 1024;
;   const float* gate = (const float*)(p.ws + OFF_MODS) + (size_t)l * 17 * 6144 + (which ? 5 : 2) * 1024;
;   for (int tile = bid(); tile < MT * 4; tile += gridDim.x) {
;     int mt, nt;
;     if (!tile_map(tile, 4, MT, mt, nt)) continue;
;     EpiRes<MB> e;
;     e.X = (_Float16*)(p.ws + OFF_X); e.gate = gate; e.row0 = mt * TR; e.n0 = nt * 256; e.ostage = (u16*)smem;
;     gemm_tile<MB>(A, lda, mt * TR, rows, W + (size_t)nt * 256 * K, K, K, smem, e, tile);
.LBB0_854:
	s_ashr_i32 s8, s0, 3
	s_lshr_b32 s9, s8, 30
	s_add_i32 s9, s8, s9
	s_ashr_i32 s9, s9, 2
	s_and_b32 s10, s0, 7
	s_lshl_b32 s11, s9, 3
	s_or_b32 s10, s11, s10
	s_cmpk_gt_i32 s10, 0xbf
	s_cbranch_scc1 .LBB0_853
	s_lshl_b32 s9, s9, 2
	s_sub_i32 s12, s8, s9
	s_waitcnt vmcnt(1)
	v_mov_b32 v124, v163
	s_mul_i32 s8, s10, 0xc0
	v_lshrrev_b32_e32 v2, 4, v124
	s_mul_i32 s10, s12, 0xb0000
	v_ashrrev_i32_e32 v0, 3, v124
	v_xor_b32_e32 v2, v2, v124
	s_ashr_i32 s11, s10, 31
	v_add_u32_e32 v3, s8, v0
	v_lshlrev_b32_e32 v2, 3, v2
	s_lshl_b64 s[10:11], s[10:11], 1
	v_and_b32_e32 v4, 56, v2
	v_med3_i32 v2, v3, 0, v208
	s_add_u32 s16, s2, s10
	v_mul_u32_u24_e32 v2, 0xb00, v2
	s_movk_i32 s10, 0xffc0
	v_or_b32_e32 v5, v2, v4
	v_med3_i32 v2, v3, s10, v209
	v_mul_i32_i24_e32 v2, 0xb00, v2
	v_or_b32_e32 v2, v2, v4
	s_movk_i32 s10, 0xff80
	v_add_u32_e32 v118, 0x2c000, v2
	v_med3_i32 v2, v3, s10, v210
	v_mul_i32_i24_e32 v2, 0xb00, v2
	s_addc_u32 s17, s3, s11
	v_or_b32_e32 v2, v2, v4
	v_add_u32_e32 v122, 0x58000, v2
	v_mov_b64_e32 v[2:3], s[16:17]
	s_movk_i32 s13, 0x1600
	v_mad_i64_i32 v[2:3], s[16:17], v0, s13, v[2:3]
	s_mul_hi_i32 s13, s0, 0x2e8ba2e9
	s_lshr_b32 s14, s13, 31
	s_ashr_i32 s13, s13, 3
	s_add_i32 s13, s13, s14
	s_mul_i32 s13, s13, 44
	v_readfirstlane_b32 s11, v124
	s_sub_i32 s16, s0, s13
	s_bfe_u32 s9, s11, 0x20006
	s_ashr_i32 s10, s11, 8
	s_lshl_b32 s18, s16, 6
	s_lshl_b32 s11, s11, 4
	v_lshlrev_b32_e32 v0, 1, v4
	s_ashr_i32 s19, s18, 31
	s_and_b32 s14, s11, 0xfffffc00
	v_lshl_add_u64 v[120:121], v[2:3], 0, v[0:1]
	s_lshl_b64 s[18:19], s[18:19], 1
	s_add_i32 s17, s14, 0x10000
	v_lshl_add_u64 v[2:3], v[120:121], 0, s[18:19]
	s_add_u32 s18, s20, s18
	v_mov_b32_e32 v0, v5
	s_addc_u32 s19, s21, s19
	v_lshlrev_b64 v[4:5], 1, v[0:1]
	v_lshl_add_u64 v[6:7], s[18:19], 0, v[4:5]
	v_mov_b32_e32 v119, v1
	s_mov_b32 m0, s14
	s_nop 0
	global_load_lds_dwordx4 v[6:7], off
	v_lshlrev_b64 v[6:7], 1, v[118:119]
	v_lshl_add_u64 v[8:9], s[18:19], 0, v[6:7]
	v_mov_b32_e32 v123, v1
	s_add_i32 s11, s14, 0x2000
	s_mov_b32 m0, s11
	s_nop 0
	global_load_lds_dwordx4 v[8:9], off
	v_lshlrev_b64 v[8:9], 1, v[122:123]
	v_lshl_add_u64 v[10:11], s[18:19], 0, v[8:9]
	s_add_i32 s11, s14, 0x4000
	s_mov_b32 m0, s11
	s_nop 0
	global_load_lds_dwordx4 v[10:11], off
	s_mov_b32 m0, s17
	s_nop 0
	global_load_lds_dwordx4 v[2:3], off
	s_mov_b64 s[40:41], 0x58000
	s_add_i32 s11, s14, 0x12000
	v_lshl_add_u64 v[10:11], v[2:3], 0, s[40:41]
	s_mov_b32 m0, s11
	s_nop 0
	global_load_lds_dwordx4 v[10:11], off
	s_mov_b64 s[48:49], 0xb0000
	s_add_i32 s11, s14, 0x14000
	v_lshl_add_u64 v[10:11], v[2:3], 0, s[48:49]
	s_mov_b32 m0, s11
	s_nop 0
	global_load_lds_dwordx4 v[10:11], off
	s_mov_b64 s[54:55], 0x108000
	s_add_i32 s11, s14, 0x16000
	v_lshl_add_u64 v[2:3], v[2:3], 0, s[54:55]
	s_mov_b32 m0, s11
	s_nop 0
	global_load_lds_dwordx4 v[2:3], off
	s_lshl_b32 s11, s9, 13
	s_bitset1_b32 s11, 16
	s_cmp_lt_i32 s16, 43
	s_cselect_b32 s18, 0, 0xffffffd4
	s_add_i32 s18, s16, s18
	s_lshl_b32 s18, s18, 6
	v_lshrrev_b32_e32 v12, 5, v124
	v_and_b32_e32 v125, 31, v124
	v_bfe_u32 v2, v124, 1, 3
	s_add_i32 s18, s18, 64
	v_lshlrev_b32_e32 v3, 7, v125
	v_bitop3_b32 v10, v12, v2, 1 bitop3:0x6c
	s_ashr_i32 s19, s18, 31
	s_waitcnt vmcnt(0)
	v_bfe_u32 v126, v124, 5, 1
	v_lshl_or_b32 v10, v10, 4, v3
	s_mul_i32 s13, s10, 0x3000
	s_lshl_b64 s[18:19], s[18:19], 1
	v_bitop3_b32 v11, v126, v2, 2 bitop3:0x36
	v_or_b32_e32 v131, s13, v10
	s_add_u32 s18, s20, s18
	s_waitcnt vmcnt(0)
	s_barrier
	v_lshl_or_b32 v129, v11, 4, v3
	v_bitop3_b32 v11, v126, v2, 4 bitop3:0x36
	v_bitop3_b32 v2, v126, v2, 6 bitop3:0x36
	ds_read_b128 v[110:113], v131
	ds_read_b128 v[106:109], v131 offset:4096
	v_or_b32_e32 v130, s11, v10
	ds_read_b128 v[98:101], v131 offset:8192
	ds_read_b128 v[114:117], v130
	ds_read_b128 v[102:105], v130 offset:4096
	s_addc_u32 s19, s21, s19
	v_lshl_or_b32 v128, v11, 4, v3
	v_lshl_or_b32 v127, v2, 4, v3
	s_add_i32 s22, s14, 0x8000
	v_lshl_add_u64 v[2:3], s[18:19], 0, v[4:5]
	s_mov_b32 m0, s22
	s_nop 0
	global_load_lds_dwordx4 v[2:3], off
	v_lshl_add_u64 v[2:3], s[18:19], 0, v[6:7]
	s_add_i32 s22, s14, 0xa000
	s_mov_b32 m0, s22
	s_nop 0
	global_load_lds_dwordx4 v[2:3], off
	v_lshl_add_u64 v[2:3], s[18:19], 0, v[8:9]
	s_add_i32 s18, s14, 0xc000
	s_mov_b32 m0, s18
	s_nop 0
	global_load_lds_dwordx4 v[2:3], off
	v_mov_b32_e32 v34, 0
	s_mov_b32 s15, 0
	s_mov_b32 s22, 0
	v_mov_b32_e32 v35, v34
	v_pk_mov_b32 v[2:3], v[34:35], v[34:35]
	v_pk_mov_b32 v[4:5], v[34:35], v[34:35]
	v_pk_mov_b32 v[6:7], v[34:35], v[34:35]
	v_pk_mov_b32 v[8:9], v[34:35], v[34:35]
	v_pk_mov_b32 v[10:11], v[34:35], v[34:35]
	v_pk_mov_b32 v[12:13], v[34:35], v[34:35]
	v_pk_mov_b32 v[14:15], v[34:35], v[34:35]
	v_pk_mov_b32 v[16:17], v[34:35], v[34:35]
	v_pk_mov_b32 v[18:19], v[34:35], v[34:35]
	v_pk_mov_b32 v[20:21], v[34:35], v[34:35]
	v_pk_mov_b32 v[22:23], v[34:35], v[34:35]
	v_pk_mov_b32 v[24:25], v[34:35], v[34:35]
	v_pk_mov_b32 v[26:27], v[34:35], v[34:35]
	v_pk_mov_b32 v[28:29], v[34:35], v[34:35]
	v_pk_mov_b32 v[30:31], v[34:35], v[34:35]
	v_pk_mov_b32 v[32:33], v[34:35], v[34:35]
	v_pk_mov_b32 v[36:37], v[34:35], v[34:35]
	v_pk_mov_b32 v[38:39], v[34:35], v[34:35]
	v_pk_mov_b32 v[40:41], v[34:35], v[34:35]
	v_pk_mov_b32 v[42:43], v[34:35], v[34:35]
	v_pk_mov_b32 v[44:45], v[34:35], v[34:35]
	v_pk_mov_b32 v[46:47], v[34:35], v[34:35]
	v_pk_mov_b32 v[48:49], v[34:35], v[34:35]
	v_pk_mov_b32 v[50:51], v[34:35], v[34:35]
	v_pk_mov_b32 v[52:53], v[34:35], v[34:35]
	v_pk_mov_b32 v[54:55], v[34:35], v[34:35]
	v_pk_mov_b32 v[56:57], v[34:35], v[34:35]
	v_pk_mov_b32 v[58:59], v[34:35], v[34:35]
	v_pk_mov_b32 v[60:61], v[34:35], v[34:35]
	v_pk_mov_b32 v[62:63], v[34:35], v[34:35]
	v_pk_mov_b32 v[64:65], v[34:35], v[34:35]
	v_pk_mov_b32 v[66:67], v[34:35], v[34:35]
	v_pk_mov_b32 v[68:69], v[34:35], v[34:35]
	v_pk_mov_b32 v[70:71], v[34:35], v[34:35]
	v_pk_mov_b32 v[72:73], v[34:35], v[34:35]
	v_pk_mov_b32 v[74:75], v[34:35], v[34:35]
	v_pk_mov_b32 v[76:77], v[34:35], v[34:35]
	v_pk_mov_b32 v[78:79], v[34:35], v[34:35]
	v_pk_mov_b32 v[80:81], v[34:35], v[34:35]
	v_pk_mov_b32 v[82:83], v[34:35], v[34:35]
	v_pk_mov_b32 v[84:85], v[34:35], v[34:35]
	v_pk_mov_b32 v[86:87], v[34:35], v[34:35]
	v_pk_mov_b32 v[88:89], v[34:35], v[34:35]
	v_pk_mov_b32 v[90:91], v[34:35], v[34:35]
	v_pk_mov_b32 v[92:93], v[34:35], v[34:35]
	v_pk_mov_b32 v[94:95], v[34:35], v[34:35]
	v_pk_mov_b32 v[96:97], v[34:35], v[34:35]

; DI int tid() { int t; asm volatile("v_mov_b32 %0, %1" : "=v"(t) : "v"((int)threadIdx.x)); return t; }
; DI int bid() { int b; asm volatile("s_mov_b32 %0, %1" : "=s"(b) : "s"((int)blockIdx.x)); return b; }
; template <int MB, class Epi>
; DI void gemm_tile(const u16* __restrict__ A, int lda, int row0, int Mrows, const u16* __restrict__ Bt, int ldb, int K, char* smem, Epi& epi, int rot) {
;     ...
;   const unsigned lds_base = (unsigned)(size_t)(lds_char*)smem;
;   const int t = tid(), lane = t & 63, w = __builtin_amdgcn_readfirstlane(t >> 6), wm = w >> 2, wn = w & 3, r = lane & 31, h = lane >> 5;
;   constexpr int NAJ = MB;
;   const int lr = t >> 3;
;   const int lch = (t & 7) ^ ((lr >> 1) & 7);
;   unsigned aoff[NAJ];
; #pragma unroll
;   for (int j = 0; j < NAJ; ++j) {
;     int gr = row0 + lr + 64 * j;
;     gr = gr < 0 ? 0 : (gr > Mrows - 1 ? Mrows - 1 : gr);
;     aoff[j] = (unsigned)gr * (unsigned)lda + lch * 8;
;   }
;   const u16* bp = Bt + (size_t)lr * ldb + lch * 8;
;   f32x16 acc[2][MB];
; #pragma unroll
;   for (int nb = 0; nb < 2; ++nb)
; #pragma unroll
;     for (int mb = 0; mb < MB; ++mb)
; #pragma unroll
;       for (int i = 0; i < 16; ++i) acc[nb][mb][i] = 0.f;
;   const int KT = K >> 6;
;   int kcur = rot % KT;
;     ...
;   GEMM_STAGE(0)
;   asm volatile("s_waitcnt vmcnt(0)" ::: "memory");
;   __syncthreads();
; template <int MB>
; DI void phase_res_t(const Params& p, int l, int which, char* smem) {
;     ...
;   for (int tile = bid(); tile < MT * 4; tile += gridDim.x) {
;     int mt, nt;
;     if (!tile_map(tile, 4, MT, mt, nt)) continue;
;     EpiRes<MB> e;
;     e.X = (_Float16*)(p.ws + OFF_X); e.gate = gate; e.row0 = mt * TR; e.n0 = nt * 256; e.ostage = (u16*)smem;
;     gemm_tile<MB>(A, lda, mt * TR, rows, W + (size_t)nt * 256 * K, K, K, smem, e, tile);
.LBB0_862:
	s_cmpk_gt_i32 s0, 0x1ff
	s_cbranch_scc1 .LBB0_867
	s_ashr_i32 s2, s0, 3
	s_lshr_b32 s3, s2, 30
	s_add_i32 s3, s2, s3
	s_ashr_i32 s3, s3, 2
	s_and_b32 s8, s0, 7
	s_lshl_b32 s9, s3, 3
	s_or_b32 s8, s9, s8
	s_cmpk_gt_i32 s8, 0x7f
	s_cbranch_scc1 .LBB0_861
	s_lshl_b32 s3, s3, 2
	s_sub_i32 s3, s2, s3
	s_lshl_b32 s2, s8, 8
	s_mul_i32 s8, s3, 0xb0000
	s_ashr_i32 s9, s8, 31
	v_mov_b32 v164, v163
	s_lshl_b64 s[8:9], s[8:9], 1
	v_lshrrev_b32_e32 v2, 4, v164
	v_ashrrev_i32_e32 v0, 3, v164
	v_xor_b32_e32 v2, v2, v164
	s_add_u32 s10, s38, s8
	v_add_u32_e32 v3, s2, v0
	v_lshlrev_b32_e32 v2, 3, v2
	s_addc_u32 s11, s39, s9
	v_and_b32_e32 v6, 56, v2
	v_med3_i32 v2, v3, 0, v211
	v_mul_u32_u24_e32 v2, 0xb00, v2
	s_movk_i32 s9, 0xffc0
	v_mov_b64_e32 v[4:5], s[10:11]
	s_movk_i32 s10, 0x1600
	v_or_b32_e32 v7, v2, v6
	v_med3_i32 v2, v3, s9, v212
	v_mad_i64_i32 v[4:5], s[10:11], v0, s10, v[4:5]
	v_mul_i32_i24_e32 v2, 0xb00, v2
	s_mul_hi_i32 s10, s0, 0x2e8ba2e9
	v_or_b32_e32 v2, v2, v6
	s_movk_i32 s9, 0xff80
	s_lshr_b32 s11, s10, 31
	s_ashr_i32 s10, s10, 3
	v_add_u32_e32 v154, 0x2c000, v2
	v_med3_i32 v2, v3, s9, v213
	s_add_i32 s10, s10, s11
	v_mul_i32_i24_e32 v2, 0xb00, v2
	s_mul_i32 s10, s10, 44
	v_readfirstlane_b32 s13, v164
	v_or_b32_e32 v2, v2, v6
	s_movk_i32 s9, 0xff40
	s_sub_i32 s14, s0, s10
	s_bfe_u32 s8, s13, 0x20006
	v_add_u32_e32 v156, 0x58000, v2
	v_med3_i32 v2, v3, s9, v214
	s_ashr_i32 s9, s13, 8
	s_lshl_b32 s10, s14, 6
	s_lshl_b32 s13, s13, 4
	v_lshlrev_b32_e32 v0, 1, v6
	s_ashr_i32 s11, s10, 31
	s_and_b32 s15, s13, 0xfffffc00
	v_lshl_add_u64 v[158:159], v[4:5], 0, v[0:1]
	s_lshl_b64 s[10:11], s[10:11], 1
	s_add_i32 s13, s15, 0x10000
	v_mul_i32_i24_e32 v2, 0xb00, v2
	v_lshl_add_u64 v[4:5], v[158:159], 0, s[10:11]
	s_add_u32 s10, s20, s10
	v_mov_b32_e32 v0, v7
	v_or_b32_e32 v2, v2, v6
	s_addc_u32 s11, s21, s11
	v_lshlrev_b64 v[6:7], 1, v[0:1]
	v_lshl_add_u64 v[8:9], s[10:11], 0, v[6:7]
	v_mov_b32_e32 v155, v1
	s_mov_b32 m0, s15
	s_nop 0
	global_load_lds_dwordx4 v[8:9], off
	v_lshlrev_b64 v[8:9], 1, v[154:155]
	v_lshl_add_u64 v[10:11], s[10:11], 0, v[8:9]
	v_mov_b32_e32 v157, v1
	v_add_u32_e32 v2, 0x84000, v2
	s_add_i32 s16, s15, 0x2000
	s_mov_b32 m0, s16
	s_nop 0
	global_load_lds_dwordx4 v[10:11], off
	v_lshlrev_b64 v[10:11], 1, v[156:157]
	v_mov_b32_e32 v3, v1
	v_lshl_add_u64 v[12:13], s[10:11], 0, v[10:11]
	s_add_i32 s16, s15, 0x4000
	s_mov_b32 m0, s16
	s_nop 0
	global_load_lds_dwordx4 v[12:13], off
	v_lshlrev_b64 v[2:3], 1, v[2:3]
	v_lshl_add_u64 v[12:13], s[10:11], 0, v[2:3]
	s_add_i32 s16, s15, 0x6000
	s_mov_b32 m0, s16
	s_nop 0
	global_load_lds_dwordx4 v[12:13], off
	s_mov_b32 m0, s13
	s_nop 0
	global_load_lds_dwordx4 v[4:5], off
	s_mov_b64 s[36:37], 0x58000
	s_add_i32 s10, s15, 0x12000
	v_lshl_add_u64 v[12:13], v[4:5], 0, s[36:37]
	s_mov_b32 m0, s10
	s_nop 0
	global_load_lds_dwordx4 v[12:13], off
	s_mov_b64 s[40:41], 0xb0000
	s_add_i32 s10, s15, 0x14000
	v_lshl_add_u64 v[12:13], v[4:5], 0, s[40:41]
	s_mov_b32 m0, s10
	s_nop 0
	global_load_lds_dwordx4 v[12:13], off
	s_mov_b64 s[48:49], 0x108000
	s_add_i32 s10, s15, 0x16000
	v_lshl_add_u64 v[4:5], v[4:5], 0, s[48:49]
	s_mov_b32 m0, s10
	s_nop 0
	global_load_lds_dwordx4 v[4:5], off
	s_lshl_b32 s10, s8, 13
	s_lshl_b32 s11, s9, 14
	s_bitset1_b32 s10, 16
	s_cmp_lt_i32 s14, 43
	s_cselect_b32 s17, 0, 0xffffffd4
	s_add_i32 s17, s14, s17
	v_lshrrev_b32_e32 v14, 5, v164
	v_and_b32_e32 v165, 31, v164
	v_bfe_u32 v4, v164, 1, 3
	s_lshl_b32 s17, s17, 6
	v_lshlrev_b32_e32 v5, 7, v165
	v_bitop3_b32 v12, v14, v4, 1 bitop3:0x6c
	s_add_i32 s18, s17, 64
	v_lshl_or_b32 v12, v12, 4, v5
	s_ashr_i32 s19, s18, 31
	v_bfe_u32 v166, v164, 5, 1
	v_or_b32_e32 v168, s11, v12
	s_lshl_b64 s[18:19], s[18:19], 1
	s_waitcnt vmcnt(0)
	s_barrier
; template <int MB, class Epi>
; DI void gemm_tile(const u16* __restrict__ A, int lda, int row0, int Mrows, const u16* __restrict__ Bt, int ldb, int K, char* smem, Epi& epi, int rot) {
;     ...
;   f32x16 acc[2][MB];
; #pragma unroll
;   for (int nb = 0; nb < 2; ++nb)
; #pragma unroll
;     for (int mb = 0; mb < MB; ++mb)
; #pragma unroll
;       for (int i = 0; i < 16; ++i) acc[nb][mb][i] = 0.f;
;     ...
;   const int sw = (r >> 1) & 7;
;   int foff[4];
; #pragma unroll
;   for (int ks = 0; ks < 4; ++ks) foff[ks] = r * 128 + (((2 * ks + h) ^ sw) << 4);
;   bf8 af[2][MB], bfr[2][2];
;   {
;     const char* as0 = As + wm * (32 * MB) * 128;
;     const char* bs0 = Bs + wn * 64 * 128;
; #pragma unroll
;     for (int mb = 0; mb < MB; ++mb) af[0][mb] = *(const bf8*)(as0 + mb * 32 * 128 + foff[0]);
; #pragma unroll
;     for (int nb = 0; nb < 2; ++nb) bfr[0][nb] = *(const bf8*)(bs0 + nb * 32 * 128 + foff[0]);
;   }
;   const int kbase = rot % KT;
;   if (KT > 1) {
;     const int k1_ = (kbase + 1 >= KT) ? kbase + 1 - KT : kbase + 1;
;     const int ko_ = k1_ * 64;
; #pragma unroll
;     for (int pc = 0; pc < 3; ++pc) GEMM_PIECE(1, pc)
;   }
	v_bitop3_b32 v13, v166, v4, 2 bitop3:0x36
	ds_read_b128 v[146:149], v168
	ds_read_b128 v[142:145], v168 offset:4096
	ds_read_b128 v[134:137], v168 offset:8192
	s_waitcnt vmcnt(0)
	ds_read_b128 v[130:133], v168 offset:12288
	s_add_u32 s18, s20, s18
	v_lshl_or_b32 v171, v13, 4, v5
	v_bitop3_b32 v13, v166, v4, 4 bitop3:0x36
	v_bitop3_b32 v4, v166, v4, 6 bitop3:0x36
	v_or_b32_e32 v167, s10, v12
	s_addc_u32 s19, s21, s19
	v_lshl_or_b32 v170, v13, 4, v5
	v_lshl_or_b32 v169, v4, 4, v5
	ds_read_b128 v[150:153], v167
	ds_read_b128 v[138:141], v167 offset:4096
	s_add_i32 s17, s15, 0x8000
	v_lshl_add_u64 v[4:5], s[18:19], 0, v[6:7]
	s_mov_b32 m0, s17
	s_nop 0
	global_load_lds_dwordx4 v[4:5], off
	v_lshl_add_u64 v[4:5], s[18:19], 0, v[8:9]
	s_add_i32 s17, s15, 0xa000
	s_mov_b32 m0, s17
	s_nop 0
	global_load_lds_dwordx4 v[4:5], off
	v_lshl_add_u64 v[4:5], s[18:19], 0, v[10:11]
	s_add_i32 s17, s15, 0xc000
	s_mov_b32 m0, s17
	s_nop 0
	global_load_lds_dwordx4 v[4:5], off
	v_lshl_add_u64 v[160:161], s[20:21], 0, v[2:3]
	v_mov_b32_e32 v2, 0
	s_mov_b32 s12, 0
	s_mov_b32 s18, 0
	v_mov_b32_e32 v3, v2
	v_pk_mov_b32 v[4:5], v[2:3], v[2:3]
	v_pk_mov_b32 v[6:7], v[2:3], v[2:3]
	v_pk_mov_b32 v[8:9], v[2:3], v[2:3]
	v_pk_mov_b32 v[10:11], v[2:3], v[2:3]
	v_pk_mov_b32 v[12:13], v[2:3], v[2:3]
	v_pk_mov_b32 v[14:15], v[2:3], v[2:3]
	v_pk_mov_b32 v[16:17], v[2:3], v[2:3]
	v_pk_mov_b32 v[18:19], v[2:3], v[2:3]
	v_pk_mov_b32 v[20:21], v[2:3], v[2:3]
	v_pk_mov_b32 v[22:23], v[2:3], v[2:3]
	v_pk_mov_b32 v[24:25], v[2:3], v[2:3]
	v_pk_mov_b32 v[26:27], v[2:3], v[2:3]
	v_pk_mov_b32 v[28:29], v[2:3], v[2:3]
	v_pk_mov_b32 v[30:31], v[2:3], v[2:3]
	v_pk_mov_b32 v[32:33], v[2:3], v[2:3]
	v_pk_mov_b32 v[34:35], v[2:3], v[2:3]
	v_pk_mov_b32 v[36:37], v[2:3], v[2:3]
	v_pk_mov_b32 v[38:39], v[2:3], v[2:3]
	v_pk_mov_b32 v[40:41], v[2:3], v[2:3]
	v_pk_mov_b32 v[42:43], v[2:3], v[2:3]
	v_pk_mov_b32 v[44:45], v[2:3], v[2:3]
	v_pk_mov_b32 v[46:47], v[2:3], v[2:3]
	v_pk_mov_b32 v[48:49], v[2:3], v[2:3]
	v_pk_mov_b32 v[50:51], v[2:3], v[2:3]
	v_pk_mov_b32 v[52:53], v[2:3], v[2:3]
	v_pk_mov_b32 v[54:55], v[2:3], v[2:3]
	v_pk_mov_b32 v[56:57], v[2:3], v[2:3]
	v_pk_mov_b32 v[58:59], v[2:3], v[2:3]
	v_pk_mov_b32 v[60:61], v[2:3], v[2:3]
	v_pk_mov_b32 v[62:63], v[2:3], v[2:3]
	v_pk_mov_b32 v[64:65], v[2:3], v[2:3]
	v_pk_mov_b32 v[66:67], v[2:3], v[2:3]
	v_pk_mov_b32 v[68:69], v[2:3], v[2:3]
	v_pk_mov_b32 v[70:71], v[2:3], v[2:3]
	v_pk_mov_b32 v[72:73], v[2:3], v[2:3]
	v_pk_mov_b32 v[74:75], v[2:3], v[2:3]
	v_pk_mov_b32 v[76:77], v[2:3], v[2:3]
	v_pk_mov_b32 v[78:79], v[2:3], v[2:3]
	v_pk_mov_b32 v[80:81], v[2:3], v[2:3]
	v_pk_mov_b32 v[82:83], v[2:3], v[2:3]
	v_pk_mov_b32 v[84:85], v[2:3], v[2:3]
	v_pk_mov_b32 v[86:87], v[2:3], v[2:3]
	v_pk_mov_b32 v[88:89], v[2:3], v[2:3]
	v_pk_mov_b32 v[90:91], v[2:3], v[2:3]
	v_pk_mov_b32 v[92:93], v[2:3], v[2:3]
	v_pk_mov_b32 v[94:95], v[2:3], v[2:3]
	v_pk_mov_b32 v[96:97], v[2:3], v[2:3]
	v_pk_mov_b32 v[98:99], v[2:3], v[2:3]
	v_pk_mov_b32 v[100:101], v[2:3], v[2:3]
	v_pk_mov_b32 v[102:103], v[2:3], v[2:3]
	v_pk_mov_b32 v[104:105], v[2:3], v[2:3]
	v_pk_mov_b32 v[106:107], v[2:3], v[2:3]
	v_pk_mov_b32 v[108:109], v[2:3], v[2:3]
	v_pk_mov_b32 v[110:111], v[2:3], v[2:3]
	v_pk_mov_b32 v[112:113], v[2:3], v[2:3]
	v_pk_mov_b32 v[114:115], v[2:3], v[2:3]
	v_pk_mov_b32 v[116:117], v[2:3], v[2:3]
	v_pk_mov_b32 v[118:119], v[2:3], v[2:3]
	v_pk_mov_b32 v[120:121], v[2:3], v[2:3]
	v_pk_mov_b32 v[122:123], v[2:3], v[2:3]
	v_pk_mov_b32 v[124:125], v[2:3], v[2:3]
	v_pk_mov_b32 v[126:127], v[2:3], v[2:3]
	v_pk_mov_b32 v[128:129], v[2:3], v[2:3]
